# attention A loop: LDS-DMA piece addresses formed as scalar base + 32-bit lane offset (six 64-bit vector adds per step removed)
# baseline (speedup 1.0000x reference)
; template <int OFF> __device__ __forceinline__ s16x4 tr_read(int vb) { s16x4 r; asm volatile("ds_read_b64_tr_b16 %0, %1 offset:%2" : "=&v"(r) : "v"(vb), "i"(OFF) : "memory"); return r; }
; __device__ __forceinline__ void finishSM(f32x16& p0, f32x16& p1, float alpha, float& l_reg, bf16x8& pa0, bf16x8& pa1, bf16x8& pa2, bf16x8& pa3) {
; #pragma unroll
;   for (int r = 0; r < 16; ++r) p1[r] = __builtin_amdgcn_exp2f(p1[r]);
;   float ps = 0;
; #pragma unroll
;   for (int r = 0; r < 16; ++r) ps += p0[r];
; #pragma unroll
;   for (int r = 0; r < 16; ++r) ps += p1[r];
;   { auto rr = __builtin_amdgcn_permlane32_swap(__float_as_uint(ps), __float_as_uint(ps), false, false);
;     ps = __uint_as_float(rr[0]) + __uint_as_float(rr[1]); }
;   l_reg = l_reg * alpha + ps;
;     ...
;   ATT_PKN(p0, 0, pa0); ATT_PKN(p0, 8, pa1); ATT_PKN(p1, 0, pa2); ATT_PKN(p1, 8, pa3);
;     ...
; }
; __device__ __forceinline__ void qkt(f32x16& p0, f32x16& p1, const bf16* Ks, const bf16x8* qr, int r32, int hi, int mp, const f32x16& negm) {
; #pragma unroll
;   for (int d0 = 0; d0 < 4; ++d0) { int cb = ((mp * 4 + d0) * 16 + hi * 8) * 2;
;     bf16x8 b0 = *reinterpret_cast<const bf16x8*>((const char*)Ks + KSWZ(r32, cb));
;     bf16x8 b1 = *reinterpret_cast<const bf16x8*>((const char*)Ks + KSWZ(32 + r32, cb));
;     if (d0 == 0) { p0 = __builtin_amdgcn_mfma_f32_32x32x16_bf16(b0, qr[0], negm, 0, 0, 0); p1 = __builtin_amdgcn_mfma_f32_32x32x16_bf16(b1, qr[0], negm, 0, 0, 0); }
;     else { p0 = __builtin_amdgcn_mfma_f32_32x32x16_bf16(b0, qr[d0], p0, 0, 0, 0); p1 = __builtin_amdgcn_mfma_f32_32x32x16_bf16(b1, qr[d0], p1, 0, 0, 0); } }
; }
; __device__ __forceinline__ int v_st(int k, int c) { const int kk = k; return ((kk >> 3) * 4 + (c >> 5)) * 512 + ((kk & 7) * 32 + (c & 31)) * 2; }
; template <int D0> __device__ __forceinline__ void pv_one(f32x16& od, int vb, bf16x8 pa0, bf16x8 pa1, bf16x8 pa2, bf16x8 pa3) {
;   const s16x4 l0 = tr_read<v_rd_off(D0, 0, 0)>(vb), h0 = tr_read<v_rd_off(D0, 0, 1)>(vb), l1 = tr_read<v_rd_off(D0, 1, 0)>(vb), h1 = tr_read<v_rd_off(D0, 1, 1)>(vb);
;   const s16x4 l2 = tr_read<v_rd_off(D0, 2, 0)>(vb), h2 = tr_read<v_rd_off(D0, 2, 1)>(vb), l3 = tr_read<v_rd_off(D0, 3, 0)>(vb), h3 = tr_read<v_rd_off(D0, 3, 1)>(vb);
.LBB0_197:
	s_add_i32 s10, s39, 0
	v_add_u32_e32 v112, s10, v202
	ds_read_b128 v[236:239], v112 offset:24576
	ds_read_b128 v[112:115], v112 offset:16384
	v_add_u32_e32 v208, s10, v201
	ds_read_b128 v[68:71], v208 offset:24576
	ds_read_b128 v[72:75], v208 offset:16384
	v_add_u32_e32 v208, s10, v199
	v_exp_f32_e32 v210, v96
	v_add_f32_e32 v96, 0, v172
	v_add_f32_e32 v96, v174, v96
	s_waitcnt lgkmcnt(2)
	v_mfma_f32_32x32x16_bf16 v[128:143], v[112:115], v[158:161], v[80:95]
	v_add_f32_e32 v96, v175, v96
	v_add_f32_e32 v96, v211, v96
	v_mfma_f32_32x32x16_bf16 v[112:127], v[236:239], v[158:161], v[80:95]
	ds_read_b128 v[236:239], v208 offset:24576
	ds_read_b128 v[240:243], v208 offset:16384
	v_add_u32_e32 v208, s10, v183
	v_add_f32_e32 v96, v212, v96
	v_add_f32_e32 v96, v215, v96
	v_add_f32_e32 v96, v216, v96
	v_add_f32_e32 v96, v233, v96
	v_add_f32_e32 v96, v173, v96
	s_waitcnt lgkmcnt(2)
	v_mfma_f32_32x32x16_bf16 v[112:127], v[68:71], v[154:157], v[112:127]
	v_add_f32_e32 v96, v176, v96
	v_add_f32_e32 v96, v177, v96
	v_add_f32_e32 v96, v213, v96
	v_add_f32_e32 v96, v214, v96
	v_exp_f32_e32 v235, v97
	v_add_f32_e32 v96, v217, v96
	v_add_f32_e32 v96, v232, v96
	v_mfma_f32_32x32x16_bf16 v[128:143], v[72:75], v[154:157], v[128:143]
	ds_read_b128 v[68:71], v208 offset:24576
	ds_read_b128 v[72:75], v208 offset:16384
	v_add_f32_e32 v96, v234, v96
	v_add_f32_e32 v96, v210, v96
	v_add_f32_e32 v96, v235, v96
	v_exp_f32_e32 v244, v106
	v_exp_f32_e32 v245, v107
	s_waitcnt lgkmcnt(2)
	v_mfma_f32_32x32x16_bf16 v[112:127], v[236:239], v[150:153], v[112:127]
	v_exp_f32_e32 v246, v108
	v_exp_f32_e32 v247, v109
	v_exp_f32_e32 v248, v110
	v_exp_f32_e32 v111, v111
	v_cvt_pk_bf16_f32 v97, v175, v211
	v_cvt_pk_bf16_f32 v109, v244, v245
	v_cvt_pk_bf16_f32 v110, v246, v247
	v_mfma_f32_32x32x16_bf16 v[128:143], v[240:243], v[150:153], v[128:143]
	s_waitcnt lgkmcnt(0)
	v_mfma_f32_32x32x16_bf16 v[112:127], v[68:71], v[146:149], v[112:127]
	v_exp_f32_e32 v236, v98
	v_exp_f32_e32 v237, v99
	v_exp_f32_e32 v238, v100
	v_exp_f32_e32 v239, v101
	v_add_f32_e32 v96, v236, v96
	v_add_f32_e32 v96, v237, v96
	v_add_f32_e32 v96, v238, v96
	v_mfma_f32_32x32x16_bf16 v[128:143], v[72:75], v[146:149], v[128:143]
	v_exp_f32_e32 v240, v102
	v_exp_f32_e32 v241, v103
	v_exp_f32_e32 v242, v104
	v_exp_f32_e32 v243, v105
	v_add_f32_e32 v96, v239, v96
	v_add_f32_e32 v96, v240, v96
	v_add_f32_e32 v96, v241, v96
	v_add_f32_e32 v96, v242, v96
	v_add_f32_e32 v96, v243, v96
	v_add_f32_e32 v96, v244, v96
	v_add_f32_e32 v96, v245, v96
	v_add_f32_e32 v96, v246, v96
	v_add_f32_e32 v96, v247, v96
	v_add_f32_e32 v96, v248, v96
	v_add_f32_e32 v208, v111, v96
	v_mov_b32_e32 v209, v208
	s_nop 1
	v_permlane32_swap_b32_e32 v208, v209
	v_cvt_pk_bf16_f32 v96, v172, v174
	v_cvt_pk_bf16_f32 v98, v212, v215
	v_cvt_pk_bf16_f32 v99, v216, v233
	v_cvt_pk_bf16_f32 v100, v173, v176
	v_cvt_pk_bf16_f32 v101, v177, v213
	v_cvt_pk_bf16_f32 v102, v214, v217
	v_cvt_pk_bf16_f32 v103, v232, v234
	v_cvt_pk_bf16_f32 v104, v210, v235
	v_cvt_pk_bf16_f32 v105, v236, v237
	v_cvt_pk_bf16_f32 v106, v238, v239
	v_cvt_pk_bf16_f32 v107, v240, v241
	v_cvt_pk_bf16_f32 v108, v242, v243
	v_cvt_pk_bf16_f32 v111, v248, v111
	v_add_u32_e32 v240, s48, v205
	ds_read_b64_tr_b16 v[210:211], v240 offset:0
	ds_read_b64_tr_b16 v[212:213], v240 offset:0x800
	ds_read_b64_tr_b16 v[214:215], v240 offset:0x1000
	ds_read_b64_tr_b16 v[216:217], v240 offset:0x1800
	ds_read_b64_tr_b16 v[232:233], v240 offset:0x2000
	ds_read_b64_tr_b16 v[234:235], v240 offset:0x2800
	ds_read_b64_tr_b16 v[236:237], v240 offset:0x3000
	ds_read_b64_tr_b16 v[238:239], v240 offset:0x3800
	s_add_i32 s12, s21, s56
	s_add_u32 s98, s50, s36
	s_addc_u32 s99, s51, s37
	s_add_u32 s100, s50, 0x4030000
	s_addc_u32 s101, s51, 0
	s_add_i32 m0, s12, 0x4000
	s_add_u32 s10, s100, 0x80
	s_addc_u32 s11, s101, 0
	global_load_lds_dwordx4 v168, s[98:99]
	s_mov_b32 m0, s12
	s_nop 0
	global_load_lds_dwordx4 v188, s[100:101]
	s_add_i32 m0, s12, 0x4400
	s_nop 0
	global_load_lds_dwordx4 v170, s[98:99]
	s_add_i32 m0, s12, 0x400
	s_nop 0
	global_load_lds_dwordx4 v188, s[10:11]
	s_waitcnt lgkmcnt(0)
; #define SBAR() __builtin_amdgcn_sched_barrier(0)
; template <int OFF> __device__ __forceinline__ s16x4 tr_read(int vb) { s16x4 r; asm volatile("ds_read_b64_tr_b16 %0, %1 offset:%2" : "=&v"(r) : "v"(vb), "i"(OFF) : "memory"); return r; }
; template <bool FIRST> __device__ __forceinline__ void partialSM(f32x16& p0, f32x16& p1, float& m_reg, f32x16& negm, float& alpha) {
;   float pmax = p0[0];
; #pragma unroll
;   for (int r = 1; r < 16; ++r) pmax = fmaxf(pmax, p0[r]);
; #pragma unroll
;   for (int r = 0; r < 16; ++r) pmax = fmaxf(pmax, p1[r]);
;   { auto rr = __builtin_amdgcn_permlane32_swap(__float_as_uint(pmax), __float_as_uint(pmax), false, false);
;     pmax = fmaxf(__uint_as_float(rr[0]), __uint_as_float(rr[1])); }
;   alpha = 1.f;
;   if (FIRST || __builtin_expect(__any(pmax > THR), 0)) { const float dl = FIRST ? pmax : fmaxf(pmax, 0.f); m_reg += dl; if (!FIRST) alpha = __builtin_amdgcn_exp2f(-dl);
; template <int D0> __device__ __forceinline__ void pv_one(f32x16& od, int vb, bf16x8 pa0, bf16x8 pa1, bf16x8 pa2, bf16x8 pa3) {
;   const s16x4 l0 = tr_read<v_rd_off(D0, 0, 0)>(vb), h0 = tr_read<v_rd_off(D0, 0, 1)>(vb), l1 = tr_read<v_rd_off(D0, 1, 0)>(vb), h1 = tr_read<v_rd_off(D0, 1, 1)>(vb);
;   const s16x4 l2 = tr_read<v_rd_off(D0, 2, 0)>(vb), h2 = tr_read<v_rd_off(D0, 2, 1)>(vb), l3 = tr_read<v_rd_off(D0, 3, 0)>(vb), h3 = tr_read<v_rd_off(D0, 3, 1)>(vb);
;   asm volatile("s_waitcnt lgkmcnt(0)" ::: "memory"); SBAR();
;   od = __builtin_amdgcn_mfma_f32_32x32x16_bf16(pa0, ATT_PK(l0, h0), od, 0, 0, 0);
;   od = __builtin_amdgcn_mfma_f32_32x32x16_bf16(pa1, ATT_PK(l1, h1), od, 0, 0, 0);
;   od = __builtin_amdgcn_mfma_f32_32x32x16_bf16(pa2, ATT_PK(l2, h2), od, 0, 0, 0);
;   od = __builtin_amdgcn_mfma_f32_32x32x16_bf16(pa3, ATT_PK(l3, h3), od, 0, 0, 0);
; }
; __device__ __forceinline__ void pv_d0(f32x16* o, int vb, bf16x8 pa0, bf16x8 pa1, bf16x8 pa2, bf16x8 pa3) {
;   pv_one<0>(o[0], vb, pa0, pa1, pa2, pa3); pv_one<1>(o[1], vb, pa0, pa1, pa2, pa3); pv_one<2>(o[2], vb, pa0, pa1, pa2, pa3); pv_one<3>(o[3], vb, pa0, pa1, pa2, pa3);
; }
	s_nop 0
	v_mfma_f32_32x32x16_bf16 v[0:15], v[96:99], v[210:213], v[0:15]
	ds_read_b64_tr_b16 v[210:211], v240 offset:0x200
	ds_read_b64_tr_b16 v[212:213], v240 offset:0xa00
	v_mfma_f32_32x32x16_bf16 v[0:15], v[100:103], v[214:217], v[0:15]
	ds_read_b64_tr_b16 v[214:215], v240 offset:0x1200
	ds_read_b64_tr_b16 v[216:217], v240 offset:0x1a00
	v_mfma_f32_32x32x16_bf16 v[0:15], v[104:107], v[232:235], v[0:15]
	ds_read_b64_tr_b16 v[232:233], v240 offset:0x2200
	ds_read_b64_tr_b16 v[234:235], v240 offset:0x2a00
	v_mfma_f32_32x32x16_bf16 v[0:15], v[108:111], v[236:239], v[0:15]
	ds_read_b64_tr_b16 v[236:237], v240 offset:0x3200
	ds_read_b64_tr_b16 v[238:239], v240 offset:0x3a00
	s_waitcnt lgkmcnt(0)
	v_mfma_f32_32x32x16_bf16 v[48:63], v[96:99], v[210:213], v[48:63]
	ds_read_b64_tr_b16 v[210:211], v240 offset:0x400
	ds_read_b64_tr_b16 v[212:213], v240 offset:0xc00
	v_mfma_f32_32x32x16_bf16 v[48:63], v[100:103], v[214:217], v[48:63]
	ds_read_b64_tr_b16 v[214:215], v240 offset:0x1400
	ds_read_b64_tr_b16 v[216:217], v240 offset:0x1c00
	v_mfma_f32_32x32x16_bf16 v[48:63], v[104:107], v[232:235], v[48:63]
	ds_read_b64_tr_b16 v[232:233], v240 offset:0x2400
	ds_read_b64_tr_b16 v[234:235], v240 offset:0x2c00
	v_mfma_f32_32x32x16_bf16 v[48:63], v[108:111], v[236:239], v[48:63]
	ds_read_b64_tr_b16 v[236:237], v240 offset:0x3400
	ds_read_b64_tr_b16 v[238:239], v240 offset:0x3c00
	s_waitcnt lgkmcnt(0)
	v_mfma_f32_32x32x16_bf16 v[32:47], v[96:99], v[210:213], v[32:47]
	ds_read_b64_tr_b16 v[210:211], v240 offset:0x600
	ds_read_b64_tr_b16 v[212:213], v240 offset:0xe00
	v_mfma_f32_32x32x16_bf16 v[32:47], v[100:103], v[214:217], v[32:47]
	ds_read_b64_tr_b16 v[214:215], v240 offset:0x1600
	ds_read_b64_tr_b16 v[216:217], v240 offset:0x1e00
	v_mfma_f32_32x32x16_bf16 v[32:47], v[104:107], v[232:235], v[32:47]
	ds_read_b64_tr_b16 v[232:233], v240 offset:0x2600
	ds_read_b64_tr_b16 v[234:235], v240 offset:0x2e00
	v_mfma_f32_32x32x16_bf16 v[32:47], v[108:111], v[236:239], v[32:47]
	ds_read_b64_tr_b16 v[236:237], v240 offset:0x3600
	ds_read_b64_tr_b16 v[238:239], v240 offset:0x3e00
	s_waitcnt lgkmcnt(0)
	v_mfma_f32_32x32x16_bf16 v[16:31], v[96:99], v[210:213], v[16:31]
	v_max_f32_e32 v96, v129, v129
	v_max_f32_e32 v97, v128, v128
	v_max_f32_e32 v96, v97, v96
	v_max3_f32 v96, v96, v130, v131
	v_max3_f32 v96, v96, v132, v133
	v_max3_f32 v96, v96, v134, v135
	v_max3_f32 v96, v96, v136, v137
	v_mfma_f32_32x32x16_bf16 v[16:31], v[100:103], v[214:217], v[16:31]
	v_max3_f32 v96, v96, v138, v139
	v_max3_f32 v96, v96, v140, v141
	v_max3_f32 v96, v96, v142, v143
	v_max3_f32 v96, v96, v112, v113
	v_max3_f32 v96, v96, v114, v115
	v_max3_f32 v96, v96, v116, v117
	v_max3_f32 v96, v96, v118, v119
	v_mfma_f32_32x32x16_bf16 v[16:31], v[104:107], v[232:235], v[16:31]
	v_max3_f32 v96, v96, v120, v121
	v_max3_f32 v96, v96, v122, v123
	v_max3_f32 v96, v96, v124, v125
	v_max3_f32 v96, v96, v126, v127
	v_mov_b32_e32 v97, v96
	s_nop 1
	v_permlane32_swap_b32_e32 v96, v97
	v_mfma_f32_32x32x16_bf16 v[16:31], v[108:111], v[236:239], v[16:31]
	v_max_f32_e32 v97, v97, v97
	v_max_f32_e32 v96, v96, v96
	v_max_f32_e32 v96, v96, v97
	v_cmp_lt_f32_e32 vcc, s19, v96
	s_cbranch_vccnz .LBB0_215
	v_mov_b32_e32 v210, 1.0
	v_cmp_gt_f32_e32 vcc, 1.0, v210
	s_cbranch_vccz .LBB0_202

; template <bool FIRST> __device__ __forceinline__ void partialSM(f32x16& p0, f32x16& p1, float& m_reg, f32x16& negm, float& alpha) {
;     ...
;   for (int r = 0; r < 16; ++r) p0[r] = __builtin_amdgcn_exp2f(p0[r]);
; }
; __device__ __forceinline__ void finishSM(f32x16& p0, f32x16& p1, float alpha, float& l_reg, bf16x8& pa0, bf16x8& pa1, bf16x8& pa2, bf16x8& pa3) {
; #pragma unroll
;   for (int r = 0; r < 16; ++r) p1[r] = __builtin_amdgcn_exp2f(p1[r]);
;   float ps = 0;
; #pragma unroll
;   for (int r = 0; r < 16; ++r) ps += p0[r];
; #pragma unroll
;   for (int r = 0; r < 16; ++r) ps += p1[r];
;   { auto rr = __builtin_amdgcn_permlane32_swap(__float_as_uint(ps), __float_as_uint(ps), false, false);
;     ps = __uint_as_float(rr[0]) + __uint_as_float(rr[1]); }
;   l_reg = l_reg * alpha + ps;
;     ...
;   ATT_PKN(p0, 0, pa0); ATT_PKN(p0, 8, pa1); ATT_PKN(p1, 0, pa2); ATT_PKN(p1, 8, pa3);
;     ...
; }
; __device__ __forceinline__ void qkt(f32x16& p0, f32x16& p1, const bf16* Ks, const bf16x8* qr, int r32, int hi, int mp, const f32x16& negm) {
; #pragma unroll
;   for (int d0 = 0; d0 < 4; ++d0) { int cb = ((mp * 4 + d0) * 16 + hi * 8) * 2;
;     bf16x8 b0 = *reinterpret_cast<const bf16x8*>((const char*)Ks + KSWZ(r32, cb));
;     bf16x8 b1 = *reinterpret_cast<const bf16x8*>((const char*)Ks + KSWZ(32 + r32, cb));
;     if (d0 == 0) { p0 = __builtin_amdgcn_mfma_f32_32x32x16_bf16(b0, qr[0], negm, 0, 0, 0); p1 = __builtin_amdgcn_mfma_f32_32x32x16_bf16(b1, qr[0], negm, 0, 0, 0); }
;     else { p0 = __builtin_amdgcn_mfma_f32_32x32x16_bf16(b0, qr[d0], p0, 0, 0, 0); p1 = __builtin_amdgcn_mfma_f32_32x32x16_bf16(b1, qr[d0], p1, 0, 0, 0); } }
; }
; __device__ __forceinline__ int v_st(int k, int c) { const int kk = k; return ((kk >> 3) * 4 + (c >> 5)) * 512 + ((kk & 7) * 32 + (c & 31)) * 2; }
; template <int D0> __device__ __forceinline__ void pv_one(f32x16& od, int vb, bf16x8 pa0, bf16x8 pa1, bf16x8 pa2, bf16x8 pa3) {
;   const s16x4 l0 = tr_read<v_rd_off(D0, 0, 0)>(vb), h0 = tr_read<v_rd_off(D0, 0, 1)>(vb), l1 = tr_read<v_rd_off(D0, 1, 0)>(vb), h1 = tr_read<v_rd_off(D0, 1, 1)>(vb);
;   const s16x4 l2 = tr_read<v_rd_off(D0, 2, 0)>(vb), h2 = tr_read<v_rd_off(D0, 2, 1)>(vb), l3 = tr_read<v_rd_off(D0, 3, 0)>(vb), h3 = tr_read<v_rd_off(D0, 3, 1)>(vb);
.LBB0_202:
	v_exp_f32_e32 v211, v128
	v_exp_f32_e32 v213, v129
	v_exp_f32_e32 v214, v130
	v_exp_f32_e32 v217, v131
	v_exp_f32_e32 v232, v132
	v_exp_f32_e32 v235, v133
	v_exp_f32_e32 v236, v134
	v_exp_f32_e32 v239, v135
	v_exp_f32_e32 v212, v136
	v_exp_f32_e32 v215, v137
	v_exp_f32_e32 v216, v138
	v_exp_f32_e32 v233, v139
	v_exp_f32_e32 v234, v140
	v_exp_f32_e32 v237, v141
	v_exp_f32_e32 v238, v142
	v_exp_f32_e32 v240, v143
	s_waitcnt vmcnt(4) lgkmcnt(0)
	s_barrier
	s_add_i32 s10, s39, 0x8000
	s_and_b32 s48, s10, 0x1ffff
	s_add_i32 s10, s48, 0
	v_add_u32_e32 v96, s10, v202
	ds_read_b128 v[242:245], v96 offset:24576
	ds_read_b128 v[96:99], v96 offset:16384
	v_add_u32_e32 v241, s10, v201
	v_exp_f32_e32 v112, v112
	v_exp_f32_e32 v115, v115
	v_exp_f32_e32 v116, v116
	s_waitcnt lgkmcnt(0)
	v_mfma_f32_32x32x16_bf16 v[128:143], v[96:99], v[158:161], v[80:95]
	v_exp_f32_e32 v117, v117
	v_exp_f32_e32 v118, v118
	v_mfma_f32_32x32x16_bf16 v[96:111], v[242:245], v[158:161], v[80:95]
	ds_read_b128 v[242:245], v241 offset:24576
	ds_read_b128 v[246:249], v241 offset:16384
	v_add_u32_e32 v241, s10, v199
	ds_read_b128 v[68:71], v241 offset:24576
	ds_read_b128 v[72:75], v241 offset:16384
	v_add_u32_e32 v241, s10, v183
	s_waitcnt lgkmcnt(2)
	v_mfma_f32_32x32x16_bf16 v[128:143], v[246:249], v[154:157], v[128:143]
	v_mfma_f32_32x32x16_bf16 v[96:111], v[242:245], v[154:157], v[96:111]
	ds_read_b128 v[242:245], v241 offset:24576
	ds_read_b128 v[246:249], v241 offset:16384
	s_waitcnt lgkmcnt(2)
	v_mfma_f32_32x32x16_bf16 v[128:143], v[72:75], v[150:153], v[128:143]
	v_mfma_f32_32x32x16_bf16 v[96:111], v[68:71], v[150:153], v[96:111]
	v_exp_f32_e32 v241, v113
	v_add_f32_e32 v113, 0, v211
	v_add_f32_e32 v113, v213, v113
	v_add_f32_e32 v113, v214, v113
	v_add_f32_e32 v113, v217, v113
	v_add_f32_e32 v113, v232, v113
	v_add_f32_e32 v113, v235, v113
	v_add_f32_e32 v113, v236, v113
	v_add_f32_e32 v113, v239, v113
	v_add_f32_e32 v113, v212, v113
	v_add_f32_e32 v113, v215, v113
	v_add_f32_e32 v113, v216, v113
	v_add_f32_e32 v113, v233, v113
	v_add_f32_e32 v113, v234, v113
	v_add_f32_e32 v113, v237, v113
	s_waitcnt lgkmcnt(0)
	v_mfma_f32_32x32x16_bf16 v[96:111], v[242:245], v[146:149], v[96:111]
	v_exp_f32_e32 v242, v114
	v_add_f32_e32 v113, v238, v113
	v_add_f32_e32 v113, v240, v113
	v_add_f32_e32 v113, v112, v113
	v_add_f32_e32 v113, v241, v113
	v_add_f32_e32 v113, v242, v113
	v_exp_f32_e32 v243, v119
	v_add_f32_e32 v113, v115, v113
	v_exp_f32_e32 v119, v120
	v_add_f32_e32 v113, v116, v113
	v_exp_f32_e32 v120, v121
	v_add_f32_e32 v113, v117, v113
	v_exp_f32_e32 v121, v122
	v_add_f32_e32 v113, v118, v113
	v_exp_f32_e32 v122, v123
	v_add_f32_e32 v113, v243, v113
	v_exp_f32_e32 v123, v124
	v_add_f32_e32 v113, v119, v113
	v_exp_f32_e32 v124, v125
	v_add_f32_e32 v113, v120, v113
	v_mfma_f32_32x32x16_bf16 v[128:143], v[246:249], v[146:149], v[128:143]
	v_exp_f32_e32 v125, v126
	v_add_f32_e32 v113, v121, v113
	v_exp_f32_e32 v126, v127
	v_add_f32_e32 v113, v122, v113
	v_add_f32_e32 v113, v123, v113
	v_add_f32_e32 v113, v124, v113
	v_add_f32_e32 v113, v125, v113
	v_add_f32_e32 v113, v126, v113
	v_mov_b32_e32 v114, v113
	s_nop 1
	v_permlane32_swap_b32_e32 v113, v114
	v_cvt_pk_bf16_f32 v250, v211, v213
	v_cvt_pk_bf16_f32 v251, v214, v217
	v_cvt_pk_bf16_f32 v252, v232, v235
	v_cvt_pk_bf16_f32 v253, v236, v239
	v_cvt_pk_bf16_f32 v212, v212, v215
	v_cvt_pk_bf16_f32 v213, v216, v233
	v_cvt_pk_bf16_f32 v214, v234, v237
	v_cvt_pk_bf16_f32 v215, v238, v240
	v_cvt_pk_bf16_f32 v232, v112, v241
	v_cvt_pk_bf16_f32 v233, v242, v115
	v_cvt_pk_bf16_f32 v234, v116, v117
	v_cvt_pk_bf16_f32 v235, v118, v243
	v_cvt_pk_bf16_f32 v116, v119, v120
	v_cvt_pk_bf16_f32 v117, v121, v122
	v_cvt_pk_bf16_f32 v118, v123, v124
	v_cvt_pk_bf16_f32 v119, v125, v126
	v_add_u32_e32 v112, s39, v205
	ds_read_b64_tr_b16 v[120:121], v112 offset:0
	ds_read_b64_tr_b16 v[122:123], v112 offset:0x800
	ds_read_b64_tr_b16 v[124:125], v112 offset:0x1000
	ds_read_b64_tr_b16 v[126:127], v112 offset:0x1800
	ds_read_b64_tr_b16 v[236:237], v112 offset:0x2000
	ds_read_b64_tr_b16 v[238:239], v112 offset:0x2800
	ds_read_b64_tr_b16 v[240:241], v112 offset:0x3000
	ds_read_b64_tr_b16 v[242:243], v112 offset:0x3800
	s_cmp_gt_u32 s44, 60
	s_cselect_b64 s[52:53], -1, 0
	s_and_b64 vcc, exec, s[52:53]
	s_cbranch_vccnz .LBB0_204
	s_add_i32 s10, s56, 0x8000
	s_and_b32 s10, s10, 0x1ffff
	s_add_i32 s12, s21, s10
	s_add_u32 s98, s50, s68
	s_addc_u32 s99, s51, s69
	s_add_u32 s100, s50, 0x4040000
	s_addc_u32 s101, s51, 0
	s_add_i32 m0, s12, 0x4000
	s_add_u32 s10, s100, 0x80
	s_addc_u32 s11, s101, 0
	global_load_lds_dwordx4 v168, s[98:99]
	s_mov_b32 m0, s12
	s_nop 0
	global_load_lds_dwordx4 v188, s[100:101]
	s_add_i32 m0, s12, 0x4400
	s_nop 0
	global_load_lds_dwordx4 v170, s[98:99]
	s_add_i32 m0, s12, 0x400
	s_nop 0
	global_load_lds_dwordx4 v188, s[10:11]

; __global__ void __launch_bounds__(512, 2) mega(Args a) {
;     extern __shared__ __attribute__((aligned(16))) unsigned char lds[];
	.amdhsa_kernel _Z4mega4Args
		.amdhsa_group_segment_fixed_size 0
		.amdhsa_private_segment_fixed_size 0
		.amdhsa_kernarg_size 384
		.amdhsa_user_sgpr_count 2
		.amdhsa_user_sgpr_dispatch_ptr 0
		.amdhsa_user_sgpr_queue_ptr 0
		.amdhsa_user_sgpr_kernarg_segment_ptr 1
		.amdhsa_user_sgpr_dispatch_id 0
		.amdhsa_user_sgpr_kernarg_preload_length 0
		.amdhsa_user_sgpr_kernarg_preload_offset 0
		.amdhsa_user_sgpr_private_segment_size 0
		.amdhsa_uses_dynamic_stack 0
		.amdhsa_enable_private_segment 0
		.amdhsa_system_sgpr_workgroup_id_x 1
		.amdhsa_system_sgpr_workgroup_id_y 0
		.amdhsa_system_sgpr_workgroup_id_z 0
		.amdhsa_system_sgpr_workgroup_info 0
		.amdhsa_system_vgpr_workitem_id 2
		.amdhsa_next_free_vgpr 256
		.amdhsa_next_free_sgpr 102
		.amdhsa_accum_offset 256
		.amdhsa_reserve_vcc 1
		.amdhsa_float_round_mode_32 0
		.amdhsa_float_round_mode_16_64 0
		.amdhsa_float_denorm_mode_32 3
		.amdhsa_float_denorm_mode_16_64 3
		.amdhsa_dx10_clamp 1
		.amdhsa_ieee_mode 1
		.amdhsa_fp16_overflow 0
		.amdhsa_tg_split 0
		.amdhsa_exception_fp_ieee_invalid_op 0
		.amdhsa_exception_fp_denorm_src 0
		.amdhsa_exception_fp_ieee_div_zero 0
		.amdhsa_exception_fp_ieee_overflow 0
		.amdhsa_exception_fp_ieee_underflow 0
		.amdhsa_exception_fp_ieee_inexact 0
		.amdhsa_exception_int_div_zero 0
	.end_amdhsa_kernel

; __global__ void __launch_bounds__(512, 2) mega(Args a) {
;     extern __shared__ __attribute__((aligned(16))) unsigned char lds[];
amdhsa.kernels:
  - .agpr_count:     0
    .args:
      - .offset:         0
        .size:           128
        .value_kind:     by_value
      - .offset:         128
        .size:           4
        .value_kind:     hidden_block_count_x
      - .offset:         132
        .size:           4
        .value_kind:     hidden_block_count_y
      - .offset:         136
        .size:           4
        .value_kind:     hidden_block_count_z
      - .offset:         140
        .size:           2
        .value_kind:     hidden_group_size_x
      - .offset:         142
        .size:           2
        .value_kind:     hidden_group_size_y
      - .offset:         144
        .size:           2
        .value_kind:     hidden_group_size_z
      - .offset:         146
        .size:           2
        .value_kind:     hidden_remainder_x
      - .offset:         148
        .size:           2
        .value_kind:     hidden_remainder_y
      - .offset:         150
        .size:           2
        .value_kind:     hidden_remainder_z
      - .offset:         168
        .size:           8
        .value_kind:     hidden_global_offset_x
      - .offset:         176
        .size:           8
        .value_kind:     hidden_global_offset_y
      - .offset:         184
        .size:           8
        .value_kind:     hidden_global_offset_z
      - .offset:         192
        .size:           2
        .value_kind:     hidden_grid_dims
      - .offset:         216
        .size:           8
        .value_kind:     hidden_multigrid_sync_arg
      - .offset:         248
        .size:           4
        .value_kind:     hidden_dynamic_lds_size
    .group_segment_fixed_size: 0
    .kernarg_segment_align: 8
    .kernarg_segment_size: 384
    .language:       OpenCL C
    .language_version:
      - 2
      - 0
    .max_flat_workgroup_size: 512
    .name:           _Z4mega4Args
    .private_segment_fixed_size: 0
    .sgpr_count:     108
    .sgpr_spill_count: 107
    .symbol:         _Z4mega4Args.kd
    .uniform_work_group_size: 1
    .uses_dynamic_stack: false
    .vgpr_count:     256
    .vgpr_spill_count: 0
    .wavefront_size: 64
